# grid barrier: L1 invalidate issued at arrival (overlaps the wait) instead of after the release; plus previous attention edits
# speedup vs baseline: 1.0194x; 1.0117x over previous
; __device__ __forceinline__ unsigned xb_ld(unsigned* p)              { return __hip_atomic_load(p, __ATOMIC_RELAXED, __HIP_MEMORY_SCOPE_AGENT); }
; __device__ __forceinline__ unsigned xb_add(unsigned* p, unsigned v) { return __hip_atomic_fetch_add(p, v, __ATOMIC_RELAXED, __HIP_MEMORY_SCOPE_AGENT); }
; #define XB_SPIN(cond, bar) do { unsigned _sp = 0; while (cond) { __builtin_amdgcn_s_sleep(1); \
;     if ((++_sp & 255u) == 0u) { if (xb_ld(&(bar)[XB_TMO])) break; if (_sp > XB_SPIN_CAP) { atomicAdd(&(bar)[XB_TMO], 1u); break; } } } } while (0)
; __device__ __forceinline__ void xcd_barrier(const XcdBarrier& b) {
;     ...
;     if (threadIdx.x == 0) {
;         unsigned* bar = b.bar;
;         __builtin_amdgcn_s_waitcnt(0);
;         unsigned nloc = b.st[0], nx = b.st[1];
;         if (nloc == 0u) { xcd_barrier_complete(bar, b.x, nloc, nx); b.st[0] = nloc; b.st[1] = nx; }
;         const unsigned old = xb_add(&bar[XB_XSUB(b.x)], 1u);
;         const unsigned gen = old / nloc;
;         if (old + 1u == (gen + 1u) * nloc) {
;             __builtin_amdgcn_fence(__ATOMIC_RELEASE, "agent");
;             asm volatile("s_waitcnt vmcnt(0)" ::: "memory");
;             const unsigned og = xb_add(&bar[XB_TOP], 1u);
;             const unsigned tg = og / nx;
;             if (og + 1u == (tg + 1u) * nx) xb_add(&bar[XB_TOPGEN], 1u);
;             else XB_SPIN(xb_ld(&bar[XB_TOPGEN]) == tg, bar);
;             __builtin_amdgcn_fence(__ATOMIC_ACQUIRE, "agent");
;             xb_add(&bar[XB_XGEN(b.x)], 1u);
;             asm volatile("s_waitcnt vmcnt(0)" ::: "memory");
;         } else {
;             XB_SPIN(xb_ld(&bar[XB_XGEN(b.x)]) == gen, bar);
;             __builtin_amdgcn_fence(__ATOMIC_ACQUIRE, "agent");
;             asm volatile("s_waitcnt vmcnt(0)" ::: "memory");
;         }
.LBB0_61:
	s_lshl_b32 s4, s69, 8
	s_add_u32 s29, s33, s4
	s_addc_u32 s28, s68, 0
	v_mov_b32_e32 v1, s29
	v_add_co_u32_e32 v4, vcc, 0x1000, v1
	v_mov_b32_e32 v1, s28
	s_nop 0
	v_addc_co_u32_e32 v5, vcc, 0, v1, vcc
	v_mov_b32_e32 v1, 1
	flat_atomic_add v1, v[4:5], v1 offset:1024 sc0
	v_cvt_f32_u32_e32 v3, v2
	v_sub_u32_e32 v4, 0, v2
	v_rcp_iflag_f32_e32 v3, v3
	s_nop 0
	v_mul_f32_e32 v3, 0x4f7ffffe, v3
	v_cvt_u32_f32_e32 v3, v3
	v_mul_lo_u32 v4, v4, v3
	v_mul_hi_u32 v4, v3, v4
	v_add_u32_e32 v3, v3, v4
	s_waitcnt vmcnt(0) lgkmcnt(0)
	v_mul_hi_u32 v3, v1, v3
	v_mul_lo_u32 v5, v3, v2
	v_add_u32_e32 v4, 1, v1
	v_sub_u32_e32 v1, v1, v5
	v_add_u32_e32 v6, 1, v3
	v_cmp_ge_u32_e32 vcc, v1, v2
	v_sub_u32_e32 v5, v1, v2
	s_nop 0
	v_cndmask_b32_e32 v3, v3, v6, vcc
	v_cndmask_b32_e32 v1, v1, v5, vcc
	v_add_u32_e32 v5, 1, v3
	v_cmp_ge_u32_e32 vcc, v1, v2
	s_nop 1
	v_cndmask_b32_e32 v1, v3, v5, vcc
	v_mad_u64_u32 v[2:3], s[4:5], v2, v1, v[2:3]
	v_cmp_ne_u32_e32 vcc, v4, v2
	s_and_saveexec_b64 s[4:5], vcc
	s_xor_b64 s[4:5], exec, s[4:5]
	s_cbranch_execz .LBB0_74
	buffer_inv sc1
	v_mov_b32_e32 v0, s29
	v_add_co_u32_e32 v2, vcc, 0x2000, v0
	v_mov_b32_e32 v0, s28
	s_nop 0
	v_addc_co_u32_e32 v3, vcc, 0, v0, vcc
	flat_load_dword v0, v[2:3] offset:1024 sc1
	s_add_u32 s10, s29, 0x2400
	s_addc_u32 s11, s28, 0
	s_waitcnt vmcnt(0) lgkmcnt(0)
	v_cmp_eq_u32_e32 vcc, v0, v1
	s_and_saveexec_b64 s[6:7], vcc
	s_cbranch_execz .LBB0_73
	s_add_u32 s8, s40, 0x80200
	s_addc_u32 s9, s41, 0
	s_mov_b32 s30, 1
	s_mov_b64 s[12:13], 0
	s_branch .LBB0_65

; __device__ __forceinline__ unsigned xb_ld(unsigned* p)              { return __hip_atomic_load(p, __ATOMIC_RELAXED, __HIP_MEMORY_SCOPE_AGENT); }
; __device__ __forceinline__ unsigned xb_add(unsigned* p, unsigned v) { return __hip_atomic_fetch_add(p, v, __ATOMIC_RELAXED, __HIP_MEMORY_SCOPE_AGENT); }
; #define XB_SPIN(cond, bar) do { unsigned _sp = 0; while (cond) { __builtin_amdgcn_s_sleep(1); \
;     if ((++_sp & 255u) == 0u) { if (xb_ld(&(bar)[XB_TMO])) break; if (_sp > XB_SPIN_CAP) { atomicAdd(&(bar)[XB_TMO], 1u); break; } } } } while (0)
; __device__ __forceinline__ void xcd_barrier(const XcdBarrier& b) {
;     ...
;         const unsigned old = xb_add(&bar[XB_XSUB(b.x)], 1u);
;         const unsigned gen = old / nloc;
;         if (old + 1u == (gen + 1u) * nloc) {
;             __builtin_amdgcn_fence(__ATOMIC_RELEASE, "agent");
;             asm volatile("s_waitcnt vmcnt(0)" ::: "memory");
;             const unsigned og = xb_add(&bar[XB_TOP], 1u);
;             const unsigned tg = og / nx;
;             if (og + 1u == (tg + 1u) * nx) xb_add(&bar[XB_TOPGEN], 1u);
;             else XB_SPIN(xb_ld(&bar[XB_TOPGEN]) == tg, bar);
.LBB0_73:
	s_or_b64 exec, exec, s[6:7]
	s_waitcnt vmcnt(0) lgkmcnt(0)
	s_waitcnt vmcnt(0)
.LBB0_74:
	s_andn2_saveexec_b64 s[4:5], s[4:5]
	s_cbranch_execz .LBB0_90
	v_mov_b32_e32 v1, s40
	v_add_co_u32_e32 v2, vcc, 0x83000, v1
	v_mov_b32_e32 v1, s41
	buffer_wbl2 sc1
	s_waitcnt vmcnt(0)
	buffer_inv sc1
	v_addc_co_u32_e32 v3, vcc, 0, v1, vcc
	v_mov_b32_e32 v1, 1
	flat_atomic_add v1, v[2:3], v1 offset:1024 sc0
	v_cvt_f32_u32_e32 v2, v0
	v_sub_u32_e32 v3, 0, v0
	s_add_u32 s4, s40, 0x83500
	s_addc_u32 s5, s41, 0
	v_rcp_iflag_f32_e32 v2, v2
	s_mov_b64 s[8:9], -1
	v_mul_f32_e32 v2, 0x4f7ffffe, v2
	v_cvt_u32_f32_e32 v2, v2
	v_mul_lo_u32 v3, v3, v2
	v_mul_hi_u32 v3, v2, v3
	v_add_u32_e32 v2, v2, v3
	s_waitcnt vmcnt(0) lgkmcnt(0)
	v_mul_hi_u32 v2, v1, v2
	v_mul_lo_u32 v4, v2, v0
	v_add_u32_e32 v3, 1, v1
	v_sub_u32_e32 v1, v1, v4
	v_add_u32_e32 v5, 1, v2
	v_cmp_ge_u32_e32 vcc, v1, v0
	v_sub_u32_e32 v4, v1, v0
	s_nop 0
	v_cndmask_b32_e32 v2, v2, v5, vcc
	v_cndmask_b32_e32 v1, v1, v4, vcc
	v_add_u32_e32 v4, 1, v2
	v_cmp_ge_u32_e32 vcc, v1, v0
	s_nop 1
	v_cndmask_b32_e32 v2, v2, v4, vcc
	v_mad_u64_u32 v[0:1], s[6:7], v0, v2, v[0:1]
	v_cmp_ne_u32_e32 vcc, v3, v0
	v_mov_b64_e32 v[0:1], s[4:5]
	s_and_saveexec_b64 s[6:7], vcc
	s_cbranch_execz .LBB0_87
	v_mov_b64_e32 v[0:1], s[4:5]
	flat_load_dword v0, v[0:1] sc1
	s_mov_b64 s[12:13], 0
	s_waitcnt vmcnt(0) lgkmcnt(0)
	v_cmp_eq_u32_e32 vcc, v0, v2
	s_and_saveexec_b64 s[10:11], vcc
	s_cbranch_execz .LBB0_86
	s_add_u32 s8, s40, 0x80200
	s_addc_u32 s9, s41, 0
	s_mov_b32 s24, 1
	s_branch .LBB0_79

; __device__ __forceinline__ unsigned xb_add(unsigned* p, unsigned v) { return __hip_atomic_fetch_add(p, v, __ATOMIC_RELAXED, __HIP_MEMORY_SCOPE_AGENT); }
; __device__ __forceinline__ void xcd_barrier(const XcdBarrier& b) {
;     ...
;             __builtin_amdgcn_fence(__ATOMIC_ACQUIRE, "agent");
;             xb_add(&bar[XB_XGEN(b.x)], 1u);
;             asm volatile("s_waitcnt vmcnt(0)" ::: "memory");
.LBB0_89:
	s_or_b64 exec, exec, s[4:5]
	v_mov_b32_e32 v0, s29
	v_add_co_u32_e32 v0, vcc, 0x2000, v0
	v_mov_b32_e32 v1, s28
	s_nop 0
	v_addc_co_u32_e32 v1, vcc, 0, v1, vcc
	v_mov_b32_e32 v2, 1
	s_waitcnt vmcnt(0) lgkmcnt(0)
	flat_atomic_add v[0:1], v2 offset:1024
	s_waitcnt vmcnt(0)

; __device__ __forceinline__ unsigned xb_ld(unsigned* p)              { return __hip_atomic_load(p, __ATOMIC_RELAXED, __HIP_MEMORY_SCOPE_AGENT); }
; __device__ __forceinline__ unsigned xb_add(unsigned* p, unsigned v) { return __hip_atomic_fetch_add(p, v, __ATOMIC_RELAXED, __HIP_MEMORY_SCOPE_AGENT); }
; #define XB_SPIN(cond, bar) do { unsigned _sp = 0; while (cond) { __builtin_amdgcn_s_sleep(1); \
;     if ((++_sp & 255u) == 0u) { if (xb_ld(&(bar)[XB_TMO])) break; if (_sp > XB_SPIN_CAP) { atomicAdd(&(bar)[XB_TMO], 1u); break; } } } } while (0)
; __device__ __forceinline__ void xcd_barrier(const XcdBarrier& b) {
;     ...
;         const unsigned old = xb_add(&bar[XB_XSUB(b.x)], 1u);
;         const unsigned gen = old / nloc;
;         if (old + 1u == (gen + 1u) * nloc) {
;             __builtin_amdgcn_fence(__ATOMIC_RELEASE, "agent");
;             asm volatile("s_waitcnt vmcnt(0)" ::: "memory");
;             const unsigned og = xb_add(&bar[XB_TOP], 1u);
;             const unsigned tg = og / nx;
;             if (og + 1u == (tg + 1u) * nx) xb_add(&bar[XB_TOPGEN], 1u);
;             else XB_SPIN(xb_ld(&bar[XB_TOPGEN]) == tg, bar);
.LBB0_120:
	s_andn2_saveexec_b64 s[4:5], s[4:5]
	s_cbranch_execz .LBB0_136
	v_mov_b32_e32 v1, s40
	v_add_co_u32_e32 v2, vcc, 0x83000, v1
	v_mov_b32_e32 v1, s41
	buffer_wbl2 sc1
	s_waitcnt vmcnt(0)
	buffer_inv sc1
	v_addc_co_u32_e32 v3, vcc, 0, v1, vcc
	v_mov_b32_e32 v1, 1
	flat_atomic_add v1, v[2:3], v1 offset:1024 sc0
	v_cvt_f32_u32_e32 v2, v0
	v_sub_u32_e32 v3, 0, v0
	s_add_u32 s6, s40, 0x83500
	s_addc_u32 s7, s41, 0
	v_rcp_iflag_f32_e32 v2, v2
	s_mov_b64 s[10:11], -1
	v_mul_f32_e32 v2, 0x4f7ffffe, v2
	v_cvt_u32_f32_e32 v2, v2
	v_mul_lo_u32 v3, v3, v2
	v_mul_hi_u32 v3, v2, v3
	v_add_u32_e32 v2, v2, v3
	s_waitcnt vmcnt(0) lgkmcnt(0)
	v_mul_hi_u32 v2, v1, v2
	v_mul_lo_u32 v4, v2, v0
	v_add_u32_e32 v3, 1, v1
	v_sub_u32_e32 v1, v1, v4
	v_add_u32_e32 v5, 1, v2
	v_cmp_ge_u32_e32 vcc, v1, v0
	v_sub_u32_e32 v4, v1, v0
	s_nop 0
	v_cndmask_b32_e32 v2, v2, v5, vcc
	v_cndmask_b32_e32 v1, v1, v4, vcc
	v_add_u32_e32 v4, 1, v2
	v_cmp_ge_u32_e32 vcc, v1, v0
	s_nop 1
	v_cndmask_b32_e32 v2, v2, v4, vcc
	v_mad_u64_u32 v[0:1], s[8:9], v0, v2, v[0:1]
	v_cmp_ne_u32_e32 vcc, v3, v0
	v_mov_b64_e32 v[0:1], s[6:7]
	s_and_saveexec_b64 s[8:9], vcc
	s_cbranch_execz .LBB0_133
	v_mov_b64_e32 v[0:1], s[6:7]
	flat_load_dword v0, v[0:1] sc1
	s_mov_b64 s[14:15], 0
	s_waitcnt vmcnt(0) lgkmcnt(0)
	v_cmp_eq_u32_e32 vcc, v0, v2
	s_and_saveexec_b64 s[12:13], vcc
	s_cbranch_execz .LBB0_132
	s_add_u32 s10, s40, 0x80200
	s_addc_u32 s11, s41, 0
	s_mov_b32 s30, 1
	s_branch .LBB0_125

; __device__ __forceinline__ unsigned xb_add(unsigned* p, unsigned v) { return __hip_atomic_fetch_add(p, v, __ATOMIC_RELAXED, __HIP_MEMORY_SCOPE_AGENT); }
; __device__ __forceinline__ void xcd_barrier(const XcdBarrier& b) {
;     ...
;             __builtin_amdgcn_fence(__ATOMIC_ACQUIRE, "agent");
;             xb_add(&bar[XB_XGEN(b.x)], 1u);
;             asm volatile("s_waitcnt vmcnt(0)" ::: "memory");
.LBB0_135:
	s_or_b64 exec, exec, s[6:7]
	v_mov_b32_e32 v0, s29
	v_add_co_u32_e32 v0, vcc, 0x2000, v0
	v_mov_b32_e32 v1, s28
	s_nop 0
	v_addc_co_u32_e32 v1, vcc, 0, v1, vcc
	v_mov_b32_e32 v2, 1
	s_waitcnt vmcnt(0) lgkmcnt(0)
	flat_atomic_add v[0:1], v2 offset:1024
	s_waitcnt vmcnt(0)

; __device__ __forceinline__ unsigned xb_ld(unsigned* p)              { return __hip_atomic_load(p, __ATOMIC_RELAXED, __HIP_MEMORY_SCOPE_AGENT); }
; __device__ __forceinline__ unsigned xb_add(unsigned* p, unsigned v) { return __hip_atomic_fetch_add(p, v, __ATOMIC_RELAXED, __HIP_MEMORY_SCOPE_AGENT); }
; #define XB_SPIN(cond, bar) do { unsigned _sp = 0; while (cond) { __builtin_amdgcn_s_sleep(1); \
;     if ((++_sp & 255u) == 0u) { if (xb_ld(&(bar)[XB_TMO])) break; if (_sp > XB_SPIN_CAP) { atomicAdd(&(bar)[XB_TMO], 1u); break; } } } } while (0)
; __device__ __forceinline__ void xcd_barrier(const XcdBarrier& b) {
;     ...
;     if (threadIdx.x == 0) {
;         unsigned* bar = b.bar;
;         __builtin_amdgcn_s_waitcnt(0);
;         unsigned nloc = b.st[0], nx = b.st[1];
;         if (nloc == 0u) { xcd_barrier_complete(bar, b.x, nloc, nx); b.st[0] = nloc; b.st[1] = nx; }
;         const unsigned old = xb_add(&bar[XB_XSUB(b.x)], 1u);
;         const unsigned gen = old / nloc;
;         if (old + 1u == (gen + 1u) * nloc) {
;             __builtin_amdgcn_fence(__ATOMIC_RELEASE, "agent");
;             asm volatile("s_waitcnt vmcnt(0)" ::: "memory");
;             const unsigned og = xb_add(&bar[XB_TOP], 1u);
;             const unsigned tg = og / nx;
;             if (og + 1u == (tg + 1u) * nx) xb_add(&bar[XB_TOPGEN], 1u);
;             else XB_SPIN(xb_ld(&bar[XB_TOPGEN]) == tg, bar);
;             __builtin_amdgcn_fence(__ATOMIC_ACQUIRE, "agent");
;             xb_add(&bar[XB_XGEN(b.x)], 1u);
;             asm volatile("s_waitcnt vmcnt(0)" ::: "memory");
;         } else {
;             XB_SPIN(xb_ld(&bar[XB_XGEN(b.x)]) == gen, bar);
.LBB0_495:
	s_lshl_b32 s3, s69, 8
	s_add_u32 s29, s33, s3
	s_addc_u32 s28, s68, 0
	v_mov_b32_e32 v1, s29
	v_add_co_u32_e32 v4, vcc, 0x1000, v1
	v_mov_b32_e32 v1, s28
	s_nop 0
	v_addc_co_u32_e32 v5, vcc, 0, v1, vcc
	v_mov_b32_e32 v1, 1
	flat_atomic_add v1, v[4:5], v1 offset:1024 sc0
	v_cvt_f32_u32_e32 v3, v2
	v_sub_u32_e32 v4, 0, v2
	v_rcp_iflag_f32_e32 v3, v3
	s_nop 0
	v_mul_f32_e32 v3, 0x4f7ffffe, v3
	v_cvt_u32_f32_e32 v3, v3
	v_mul_lo_u32 v4, v4, v3
	v_mul_hi_u32 v4, v3, v4
	v_add_u32_e32 v3, v3, v4
	s_waitcnt vmcnt(0) lgkmcnt(0)
	v_mul_hi_u32 v3, v1, v3
	v_mul_lo_u32 v5, v3, v2
	v_add_u32_e32 v4, 1, v1
	v_sub_u32_e32 v1, v1, v5
	v_add_u32_e32 v6, 1, v3
	v_cmp_ge_u32_e32 vcc, v1, v2
	v_sub_u32_e32 v5, v1, v2
	s_nop 0
	v_cndmask_b32_e32 v3, v3, v6, vcc
	v_cndmask_b32_e32 v1, v1, v5, vcc
	v_add_u32_e32 v5, 1, v3
	v_cmp_ge_u32_e32 vcc, v1, v2
	s_nop 1
	v_cndmask_b32_e32 v1, v3, v5, vcc
	v_mad_u64_u32 v[2:3], s[4:5], v2, v1, v[2:3]
	v_cmp_ne_u32_e32 vcc, v4, v2
	s_and_saveexec_b64 s[4:5], vcc
	s_xor_b64 s[4:5], exec, s[4:5]
	s_cbranch_execz .LBB0_508
	buffer_inv sc1
	v_mov_b32_e32 v0, s29
	v_add_co_u32_e32 v2, vcc, 0x2000, v0
	v_mov_b32_e32 v0, s28
	s_nop 0
	v_addc_co_u32_e32 v3, vcc, 0, v0, vcc
	flat_load_dword v0, v[2:3] offset:1024 sc1
	s_add_u32 s10, s29, 0x2400
	s_addc_u32 s11, s28, 0
	s_waitcnt vmcnt(0) lgkmcnt(0)
	v_cmp_eq_u32_e32 vcc, v0, v1
	s_and_saveexec_b64 s[6:7], vcc
	s_cbranch_execz .LBB0_507
	s_add_u32 s8, s40, 0x80200
	s_addc_u32 s9, s41, 0
	s_mov_b32 s30, 1
	s_mov_b64 s[12:13], 0
	s_branch .LBB0_499

; __device__ __forceinline__ unsigned xb_ld(unsigned* p)              { return __hip_atomic_load(p, __ATOMIC_RELAXED, __HIP_MEMORY_SCOPE_AGENT); }
; __device__ __forceinline__ unsigned xb_add(unsigned* p, unsigned v) { return __hip_atomic_fetch_add(p, v, __ATOMIC_RELAXED, __HIP_MEMORY_SCOPE_AGENT); }
; #define XB_SPIN(cond, bar) do { unsigned _sp = 0; while (cond) { __builtin_amdgcn_s_sleep(1); \
;     if ((++_sp & 255u) == 0u) { if (xb_ld(&(bar)[XB_TMO])) break; if (_sp > XB_SPIN_CAP) { atomicAdd(&(bar)[XB_TMO], 1u); break; } } } } while (0)
; __device__ __forceinline__ void xcd_barrier(const XcdBarrier& b) {
;     ...
;     if (threadIdx.x == 0) {
;         unsigned* bar = b.bar;
;         __builtin_amdgcn_s_waitcnt(0);
;         unsigned nloc = b.st[0], nx = b.st[1];
;         if (nloc == 0u) { xcd_barrier_complete(bar, b.x, nloc, nx); b.st[0] = nloc; b.st[1] = nx; }
;         const unsigned old = xb_add(&bar[XB_XSUB(b.x)], 1u);
;         const unsigned gen = old / nloc;
;         if (old + 1u == (gen + 1u) * nloc) {
;             __builtin_amdgcn_fence(__ATOMIC_RELEASE, "agent");
;             asm volatile("s_waitcnt vmcnt(0)" ::: "memory");
;             const unsigned og = xb_add(&bar[XB_TOP], 1u);
;             const unsigned tg = og / nx;
;             if (og + 1u == (tg + 1u) * nx) xb_add(&bar[XB_TOPGEN], 1u);
;             else XB_SPIN(xb_ld(&bar[XB_TOPGEN]) == tg, bar);
;             __builtin_amdgcn_fence(__ATOMIC_ACQUIRE, "agent");
;             xb_add(&bar[XB_XGEN(b.x)], 1u);
;             asm volatile("s_waitcnt vmcnt(0)" ::: "memory");
;         } else {
;             XB_SPIN(xb_ld(&bar[XB_XGEN(b.x)]) == gen, bar);
.LBB0_779:
	s_lshl_b32 s2, s69, 8
	s_add_u32 s25, s33, s2
	s_addc_u32 s24, s68, 0
	v_mov_b32_e32 v1, s25
	v_add_co_u32_e32 v4, vcc, 0x1000, v1
	v_mov_b32_e32 v1, s24
	s_nop 0
	v_addc_co_u32_e32 v5, vcc, 0, v1, vcc
	v_mov_b32_e32 v1, 1
	flat_atomic_add v1, v[4:5], v1 offset:1024 sc0
	v_cvt_f32_u32_e32 v3, v2
	v_sub_u32_e32 v4, 0, v2
	v_rcp_iflag_f32_e32 v3, v3
	s_nop 0
	v_mul_f32_e32 v3, 0x4f7ffffe, v3
	v_cvt_u32_f32_e32 v3, v3
	v_mul_lo_u32 v4, v4, v3
	v_mul_hi_u32 v4, v3, v4
	v_add_u32_e32 v3, v3, v4
	s_waitcnt vmcnt(0) lgkmcnt(0)
	v_mul_hi_u32 v3, v1, v3
	v_mul_lo_u32 v5, v3, v2
	v_add_u32_e32 v4, 1, v1
	v_sub_u32_e32 v1, v1, v5
	v_add_u32_e32 v6, 1, v3
	v_cmp_ge_u32_e32 vcc, v1, v2
	v_sub_u32_e32 v5, v1, v2
	s_nop 0
	v_cndmask_b32_e32 v3, v3, v6, vcc
	v_cndmask_b32_e32 v1, v1, v5, vcc
	v_add_u32_e32 v5, 1, v3
	v_cmp_ge_u32_e32 vcc, v1, v2
	s_nop 1
	v_cndmask_b32_e32 v1, v3, v5, vcc
	v_mad_u64_u32 v[2:3], s[2:3], v2, v1, v[2:3]
	v_cmp_ne_u32_e32 vcc, v4, v2
	s_and_saveexec_b64 s[2:3], vcc
	s_xor_b64 s[2:3], exec, s[2:3]
	s_cbranch_execz .LBB0_792
	buffer_inv sc1
	v_mov_b32_e32 v0, s25
	v_add_co_u32_e32 v2, vcc, 0x2000, v0
	v_mov_b32_e32 v0, s24
	s_nop 0
	v_addc_co_u32_e32 v3, vcc, 0, v0, vcc
	flat_load_dword v0, v[2:3] offset:1024 sc1
	s_add_u32 s8, s25, 0x2400
	s_addc_u32 s9, s24, 0
	s_waitcnt vmcnt(0) lgkmcnt(0)
	v_cmp_eq_u32_e32 vcc, v0, v1
	s_and_saveexec_b64 s[4:5], vcc
	s_cbranch_execz .LBB0_791
	s_add_u32 s6, s40, 0x80200
	s_addc_u32 s7, s41, 0
	s_mov_b32 s26, 1
	s_mov_b64 s[10:11], 0
	s_branch .LBB0_783

; __device__ __forceinline__ unsigned xb_ld(unsigned* p)              { return __hip_atomic_load(p, __ATOMIC_RELAXED, __HIP_MEMORY_SCOPE_AGENT); }
; __device__ __forceinline__ unsigned xb_add(unsigned* p, unsigned v) { return __hip_atomic_fetch_add(p, v, __ATOMIC_RELAXED, __HIP_MEMORY_SCOPE_AGENT); }
; #define XB_SPIN(cond, bar) do { unsigned _sp = 0; while (cond) { __builtin_amdgcn_s_sleep(1); \
;     if ((++_sp & 255u) == 0u) { if (xb_ld(&(bar)[XB_TMO])) break; if (_sp > XB_SPIN_CAP) { atomicAdd(&(bar)[XB_TMO], 1u); break; } } } } while (0)
; __device__ __forceinline__ void xcd_barrier(const XcdBarrier& b) {
;     ...
;         const unsigned old = xb_add(&bar[XB_XSUB(b.x)], 1u);
;         const unsigned gen = old / nloc;
;         if (old + 1u == (gen + 1u) * nloc) {
;             __builtin_amdgcn_fence(__ATOMIC_RELEASE, "agent");
;             asm volatile("s_waitcnt vmcnt(0)" ::: "memory");
;             const unsigned og = xb_add(&bar[XB_TOP], 1u);
;             const unsigned tg = og / nx;
;             if (og + 1u == (tg + 1u) * nx) xb_add(&bar[XB_TOPGEN], 1u);
;             else XB_SPIN(xb_ld(&bar[XB_TOPGEN]) == tg, bar);
;             __builtin_amdgcn_fence(__ATOMIC_ACQUIRE, "agent");
;             xb_add(&bar[XB_XGEN(b.x)], 1u);
;             asm volatile("s_waitcnt vmcnt(0)" ::: "memory");
;         } else {
;             XB_SPIN(xb_ld(&bar[XB_XGEN(b.x)]) == gen, bar);
;             __builtin_amdgcn_fence(__ATOMIC_ACQUIRE, "agent");
;             asm volatile("s_waitcnt vmcnt(0)" ::: "memory");
.LBB0_791:
	s_or_b64 exec, exec, s[4:5]
	s_waitcnt vmcnt(0) lgkmcnt(0)
	s_waitcnt vmcnt(0)
.LBB0_792:
	s_andn2_saveexec_b64 s[2:3], s[2:3]
	s_cbranch_execz .LBB0_808
	v_mov_b32_e32 v1, s40
	v_add_co_u32_e32 v2, vcc, 0x83000, v1
	v_mov_b32_e32 v1, s41
	buffer_wbl2 sc1
	s_waitcnt vmcnt(0)
	buffer_inv sc1
	v_addc_co_u32_e32 v3, vcc, 0, v1, vcc
	v_mov_b32_e32 v1, 1
	flat_atomic_add v1, v[2:3], v1 offset:1024 sc0
	v_cvt_f32_u32_e32 v2, v0
	v_sub_u32_e32 v3, 0, v0
	s_add_u32 s4, s40, 0x83500
	s_addc_u32 s5, s41, 0
	v_rcp_iflag_f32_e32 v2, v2
	s_mov_b64 s[8:9], -1
	v_mul_f32_e32 v2, 0x4f7ffffe, v2
	v_cvt_u32_f32_e32 v2, v2
	v_mul_lo_u32 v3, v3, v2
	v_mul_hi_u32 v3, v2, v3
	v_add_u32_e32 v2, v2, v3
	s_waitcnt vmcnt(0) lgkmcnt(0)
	v_mul_hi_u32 v2, v1, v2
	v_mul_lo_u32 v4, v2, v0
	v_add_u32_e32 v3, 1, v1
	v_sub_u32_e32 v1, v1, v4
	v_add_u32_e32 v5, 1, v2
	v_cmp_ge_u32_e32 vcc, v1, v0
	v_sub_u32_e32 v4, v1, v0
	s_nop 0
	v_cndmask_b32_e32 v2, v2, v5, vcc
	v_cndmask_b32_e32 v1, v1, v4, vcc
	v_add_u32_e32 v4, 1, v2
	v_cmp_ge_u32_e32 vcc, v1, v0
	s_nop 1
	v_cndmask_b32_e32 v2, v2, v4, vcc
	v_mad_u64_u32 v[0:1], s[6:7], v0, v2, v[0:1]
	v_cmp_ne_u32_e32 vcc, v3, v0
	v_mov_b64_e32 v[0:1], s[4:5]
	s_and_saveexec_b64 s[6:7], vcc
	s_cbranch_execz .LBB0_805
	v_mov_b64_e32 v[0:1], s[4:5]
	flat_load_dword v0, v[0:1] sc1
	s_mov_b64 s[12:13], 0
	s_waitcnt vmcnt(0) lgkmcnt(0)
	v_cmp_eq_u32_e32 vcc, v0, v2
	s_and_saveexec_b64 s[10:11], vcc
	s_cbranch_execz .LBB0_804
	s_add_u32 s8, s40, 0x80200
	s_addc_u32 s9, s41, 0
	s_mov_b32 s26, 1
	s_branch .LBB0_797

; __device__ __forceinline__ unsigned xb_add(unsigned* p, unsigned v) { return __hip_atomic_fetch_add(p, v, __ATOMIC_RELAXED, __HIP_MEMORY_SCOPE_AGENT); }
; __device__ __forceinline__ void xcd_barrier(const XcdBarrier& b) {
;     ...
;             __builtin_amdgcn_fence(__ATOMIC_ACQUIRE, "agent");
;             xb_add(&bar[XB_XGEN(b.x)], 1u);
;             asm volatile("s_waitcnt vmcnt(0)" ::: "memory");
.LBB0_807:
	s_or_b64 exec, exec, s[4:5]
	v_mov_b32_e32 v0, s25
	v_add_co_u32_e32 v0, vcc, 0x2000, v0
	v_mov_b32_e32 v1, s24
	s_nop 0
	v_addc_co_u32_e32 v1, vcc, 0, v1, vcc
	v_mov_b32_e32 v2, 1
	s_waitcnt vmcnt(0) lgkmcnt(0)
	flat_atomic_add v[0:1], v2 offset:1024
	s_waitcnt vmcnt(0)
